# P6 epilogue: residual-tile loads of row groups 2..7 issued together at the top (were one group ahead)
# baseline (speedup 1.0000x reference)
; __device__ __forceinline__ unsigned pk2(float lo, float hi) { f32x2_t v = {lo, hi}; bf16x2_t b = __builtin_convertvector(v, bf16x2_t); return __builtin_bit_cast(unsigned, b); }
;     __device__ __forceinline__ void load(int row, int col, Pre& p) const { const size_t off = (size_t)row * 2048 + col;
;     ...
;         const u32x4 w = *(const u32x4*)(HB + off);
;         p.x0 = (f32x4){bflo(w.x), bfhi(w.x), bflo(w.y), bfhi(w.y)}; p.x1 = (f32x4){bflo(w.z), bfhi(w.z), bflo(w.w), bfhi(w.w)};
;     ...
;         p.x0 = __builtin_nontemporal_load((const f32x4*)(x + off)); p.x1 = __builtin_nontemporal_load((const f32x4*)(x + off + 4));
;     ...
;     }
;     __device__ __forceinline__ float apply(int row, int col, float (&v)[8], const Pre& p) const {
;         const size_t off = (size_t)row * 2048 + col;
;         f32x4 h0, h1; float s = 0.f;
; #pragma unroll
;         for (int i = 0; i < 4; ++i) { h0[i] = p.x0[i] + v[i]; h1[i] = p.x1[i] + v[4 + i]; s += h0[i] * h0[i] + h1[i] * h1[i]; }
;     ...
;         *(f32x4*)(H1 + off) = h0; *(f32x4*)(H1 + off + 4) = h1;
;     ...
;         u32x4 w; w.x = pk2(h0[0], h0[1]); w.y = pk2(h0[2], h0[3]); w.z = pk2(h1[0], h1[1]); w.w = pk2(h1[2], h1[3]);
;         *(u32x4*)(HB + off) = w;
;     __device__ __forceinline__ void operator()(const pg8::f32x4 (&acc)[2][2][4][2], const pg8::Unit& u, int wr, int wc, int fr, int fq) const {
;     ...
;         f.load(row0, col0, pa[0]); f.load(row0, col0 + 128, pa[1]);
; #pragma unroll
;         for (int g = 0; g < 8; ++g) {
;             const int ai = g >> 2, m = g & 3, row = row0 + ai * 128 + m * 16;
;             if (g < 7) { const int row2 = row0 + ((g + 1) >> 2) * 128 + ((g + 1) & 3) * 16;
;                 if (g & 1) { f.load(row2, col0, pa[0]); f.load(row2, col0 + 128, pa[1]); } else { f.load(row2, col0, pb[0]); f.load(row2, col0 + 128, pb[1]); } }
;             float ss = 0.f;
; #pragma unroll
;             for (int bj = 0; bj < 2; ++bj) {
;                 float v[8] = {acc[ai][bj][m][0][0], acc[ai][bj][m][0][1], acc[ai][bj][m][0][2], acc[ai][bj][m][0][3], acc[ai][bj][m][1][0], acc[ai][bj][m][1][1], acc[ai][bj][m][1][2], acc[ai][bj][m][1][3]};
;                 ss += f.apply(row, col0 + bj * 128, v, (g & 1) ? pb[bj] : pa[bj]);
;             }
;             if (F::HAS_SS) { ss += __shfl_xor(ss, 16); ss += __shfl_xor(ss, 32); if (fq == 0) atomicAdd(f.ss + row, ss); }
.LBB0_967:
	v_lshl_add_u32 v154, s2, 8, v158
	v_lshl_or_b32 v152, s24, 8, v160
	v_ashrrev_i32_e32 v155, 31, v154
	v_ashrrev_i32_e32 v153, 31, v152
	v_lshlrev_b64 v[128:129], 12, v[154:155]
	v_lshl_add_u64 v[128:129], s[82:83], 0, v[128:129]
	v_lshlrev_b64 v[130:131], 1, v[152:153]
	v_lshl_add_u64 v[176:177], v[128:129], 0, v[130:131]
	global_load_dwordx4 v[168:171], v[176:177], off
	global_load_dwordx4 v[172:175], v[176:177], off offset:256
	v_or_b32_e32 v128, 16, v154
	v_ashrrev_i32_e32 v129, 31, v128
	v_lshlrev_b64 v[128:129], 12, v[128:129]
	v_lshl_add_u64 v[128:129], s[82:83], 0, v[128:129]
	v_lshl_add_u64 v[156:157], v[128:129], 0, v[130:131]
	global_load_dwordx4 v[132:135], v[156:157], off
	global_load_dwordx4 v[128:131], v[156:157], off offset:256
	v_lshlrev_b32_e32 v185, 12, v154
	v_lshl_add_u32 v185, v152, 1, v185
	v_add_u32_e32 v187, 0x20000, v185
	global_load_dwordx4 v[190:193], v187, s[82:83]
	global_load_dwordx4 v[194:197], v187, s[82:83] offset:256
	v_add_u32_e32 v187, 0x30000, v185
	global_load_dwordx4 v[198:201], v187, s[82:83]
	global_load_dwordx4 v[202:205], v187, s[82:83] offset:256
	v_add_u32_e32 v187, 0x80000, v185
	global_load_dwordx4 v[206:209], v187, s[82:83]
	global_load_dwordx4 v[210:213], v187, s[82:83] offset:256
	v_add_u32_e32 v187, 0x90000, v185
	global_load_dwordx4 v[214:217], v187, s[82:83]
	global_load_dwordx4 v[218:221], v187, s[82:83] offset:256
	v_add_u32_e32 v187, 0xa0000, v185
	global_load_dwordx4 v[222:225], v187, s[82:83]
	v_and_b32_e32 v166, 64, v164
	v_xor_b32_e32 v165, 16, v164
	v_add_u32_e32 v166, 64, v166
	v_cmp_lt_i32_e32 vcc, v165, v166
	v_xor_b32_e32 v167, 32, v164
	s_waitcnt vmcnt(11)
	v_lshlrev_b32_e32 v178, 16, v168
	v_and_b32_e32 v179, 0xffff0000, v168
	v_lshlrev_b32_e32 v180, 16, v170
	v_and_b32_e32 v181, 0xffff0000, v170
	v_lshlrev_b32_e32 v168, 16, v169
	v_and_b32_e32 v169, 0xffff0000, v169
	v_lshlrev_b32_e32 v188, 16, v174
	v_and_b32_e32 v189, 0xffff0000, v174
	v_lshlrev_b32_e32 v170, 16, v171
	v_and_b32_e32 v171, 0xffff0000, v171
	v_lshlrev_b32_e32 v182, 16, v172
	v_and_b32_e32 v183, 0xffff0000, v172
	v_lshlrev_b32_e32 v172, 16, v173
	v_and_b32_e32 v173, 0xffff0000, v173
	v_lshlrev_b32_e32 v174, 16, v175
	v_and_b32_e32 v175, 0xffff0000, v175
	v_pk_add_f32 v[120:121], v[120:121], v[180:181]
	v_pk_add_f32 v[126:127], v[126:127], v[168:169]
	v_pk_add_f32 v[168:169], v[112:113], v[188:189]
	v_pk_add_f32 v[124:125], v[124:125], v[178:179]
	v_pk_add_f32 v[122:123], v[122:123], v[170:171]
	v_pk_add_f32 v[116:117], v[116:117], v[182:183]
	v_pk_add_f32 v[118:119], v[118:119], v[172:173]
	v_pk_add_f32 v[170:171], v[114:115], v[174:175]
	v_pk_mul_f32 v[172:173], v[120:121], v[120:121]
	v_cvt_pk_bf16_f32 v114, v120, v121
	v_pk_mul_f32 v[120:121], v[168:169], v[168:169]
	v_pk_mul_f32 v[174:175], v[122:123], v[122:123]
	v_cvt_pk_bf16_f32 v112, v124, v125
	v_pk_mul_f32 v[178:179], v[170:171], v[170:171]
	v_pk_fma_f32 v[124:125], v[124:125], v[124:125], v[172:173]
	v_pk_fma_f32 v[120:121], v[116:117], v[116:117], v[120:121]
	v_cvt_pk_bf16_f32 v113, v126, v127
	v_pk_fma_f32 v[126:127], v[126:127], v[126:127], v[174:175]
	v_pk_fma_f32 v[172:173], v[118:119], v[118:119], v[178:179]
	v_add_f32_e32 v115, v120, v121
	v_add_f32_e32 v120, v124, v125
	v_add_f32_e32 v115, v172, v115
	v_add_f32_e32 v120, v126, v120
	v_cndmask_b32_e32 v165, v164, v165, vcc
	v_add_f32_e32 v115, v173, v115
	v_add_f32_e32 v120, v127, v120
	v_cmp_lt_i32_e32 vcc, v167, v166
	v_lshlrev_b32_e32 v166, 2, v165
	v_add_f32_e32 v120, v120, v115
	ds_bpermute_b32 v121, v166, v120
	v_cndmask_b32_e32 v167, v164, v167, vcc
	v_cvt_pk_bf16_f32 v115, v122, v123
	v_lshlrev_b32_e32 v165, 2, v167
	global_store_dwordx4 v[176:177], v[112:115], off
	s_waitcnt lgkmcnt(0)
	s_nop 0
	v_add_f32_e32 v112, v120, v121
	ds_bpermute_b32 v113, v165, v112
	v_cvt_pk_bf16_f32 v114, v116, v117
	v_cvt_pk_bf16_f32 v115, v118, v119
	v_cvt_pk_bf16_f32 v116, v168, v169
	v_cvt_pk_bf16_f32 v117, v170, v171
	v_lshl_add_u64 v[120:121], v[154:155], 2, s[88:89]
	global_store_dwordx4 v[176:177], v[114:117], off offset:256
	s_and_saveexec_b64 s[2:3], s[4:5]
	s_cbranch_execz .LBB0_969
	s_waitcnt lgkmcnt(0)
	v_add_f32_e32 v112, v112, v113
	v_mov_b32_e32 v230, v112
.LBB0_969:
	s_or_b64 exec, exec, s[2:3]
	v_or_b32_e32 v112, 32, v154
	s_waitcnt lgkmcnt(0)
	v_ashrrev_i32_e32 v113, 31, v112
	v_lshlrev_b64 v[112:113], 12, v[112:113]
	v_lshl_add_u64 v[112:113], s[82:83], 0, v[112:113]
	v_lshl_add_u64 v[122:123], v[152:153], 1, v[112:113]
	s_waitcnt vmcnt(9)
	v_mov_b32_e32 v116, v190
	v_mov_b32_e32 v117, v191
	v_mov_b32_e32 v118, v192
	v_mov_b32_e32 v119, v193
	v_mov_b32_e32 v112, v194
	v_mov_b32_e32 v113, v195
	v_mov_b32_e32 v114, v196
	v_mov_b32_e32 v115, v197
	v_lshlrev_b32_e32 v124, 16, v132
	v_and_b32_e32 v125, 0xffff0000, v132
	v_lshlrev_b32_e32 v126, 16, v133
	v_and_b32_e32 v127, 0xffff0000, v133
	v_lshlrev_b32_e32 v132, 16, v134
	v_and_b32_e32 v133, 0xffff0000, v134
	v_lshlrev_b32_e32 v134, 16, v135
	v_and_b32_e32 v135, 0xffff0000, v135
	v_pk_add_f32 v[108:109], v[108:109], v[124:125]
	v_pk_add_f32 v[124:125], v[104:105], v[132:133]
	v_pk_add_f32 v[110:111], v[110:111], v[126:127]
	v_pk_mul_f32 v[104:105], v[124:125], v[124:125]
	v_pk_add_f32 v[126:127], v[106:107], v[134:135]
	v_lshlrev_b32_e32 v170, 16, v130
	v_and_b32_e32 v171, 0xffff0000, v130
	v_pk_fma_f32 v[132:133], v[108:109], v[108:109], v[104:105]
	v_pk_mul_f32 v[104:105], v[126:127], v[126:127]
	v_lshlrev_b32_e32 v168, 16, v128
	v_and_b32_e32 v169, 0xffff0000, v128
	v_lshlrev_b32_e32 v130, 16, v131
	v_and_b32_e32 v131, 0xffff0000, v131
	v_pk_fma_f32 v[106:107], v[110:111], v[110:111], v[104:105]
	v_cvt_pk_bf16_f32 v104, v108, v109
	v_pk_add_f32 v[108:109], v[96:97], v[170:171]
	v_lshlrev_b32_e32 v128, 16, v129
	v_and_b32_e32 v129, 0xffff0000, v129
	v_cvt_pk_bf16_f32 v105, v110, v111
	v_pk_add_f32 v[100:101], v[100:101], v[168:169]
	v_pk_mul_f32 v[96:97], v[108:109], v[108:109]
	v_pk_add_f32 v[110:111], v[98:99], v[130:131]
	v_pk_fma_f32 v[96:97], v[100:101], v[100:101], v[96:97]
	v_pk_add_f32 v[102:103], v[102:103], v[128:129]
	v_pk_mul_f32 v[98:99], v[110:111], v[110:111]
	v_add_f32_e32 v96, v96, v97
	v_pk_fma_f32 v[98:99], v[102:103], v[102:103], v[98:99]
	v_add_f32_e32 v97, v132, v133
	v_add_f32_e32 v96, v98, v96
	v_add_f32_e32 v97, v106, v97
	v_add_f32_e32 v96, v99, v96
	v_add_f32_e32 v97, v107, v97
	v_add_f32_e32 v96, v97, v96
	ds_bpermute_b32 v97, v166, v96
	v_cvt_pk_bf16_f32 v106, v124, v125
	v_cvt_pk_bf16_f32 v107, v126, v127
	v_cvt_pk_bf16_f32 v98, v100, v101
	v_cvt_pk_bf16_f32 v99, v102, v103
	s_waitcnt lgkmcnt(0)
	v_add_f32_e32 v96, v96, v97
	ds_bpermute_b32 v97, v165, v96
	v_cvt_pk_bf16_f32 v100, v108, v109
	v_cvt_pk_bf16_f32 v101, v110, v111
	global_store_dwordx4 v[156:157], v[104:107], off
	global_store_dwordx4 v[156:157], v[98:101], off offset:256
	s_and_saveexec_b64 s[2:3], s[4:5]
	s_cbranch_execz .LBB0_971
	s_waitcnt lgkmcnt(0)
	v_add_f32_e32 v96, v96, v97
	v_mov_b32_e32 v231, v96
; __device__ __forceinline__ unsigned pk2(float lo, float hi) { f32x2_t v = {lo, hi}; bf16x2_t b = __builtin_convertvector(v, bf16x2_t); return __builtin_bit_cast(unsigned, b); }
;     __device__ __forceinline__ void load(int row, int col, Pre& p) const { const size_t off = (size_t)row * 2048 + col;
;     ...
;         const u32x4 w = *(const u32x4*)(HB + off);
;         p.x0 = (f32x4){bflo(w.x), bfhi(w.x), bflo(w.y), bfhi(w.y)}; p.x1 = (f32x4){bflo(w.z), bfhi(w.z), bflo(w.w), bfhi(w.w)};
;     ...
;         p.x0 = __builtin_nontemporal_load((const f32x4*)(x + off)); p.x1 = __builtin_nontemporal_load((const f32x4*)(x + off + 4));
;     ...
;     }
;     __device__ __forceinline__ float apply(int row, int col, float (&v)[8], const Pre& p) const {
;         const size_t off = (size_t)row * 2048 + col;
;         f32x4 h0, h1; float s = 0.f;
; #pragma unroll
;         for (int i = 0; i < 4; ++i) { h0[i] = p.x0[i] + v[i]; h1[i] = p.x1[i] + v[4 + i]; s += h0[i] * h0[i] + h1[i] * h1[i]; }
;     ...
;         *(f32x4*)(H1 + off) = h0; *(f32x4*)(H1 + off + 4) = h1;
;     ...
;         u32x4 w; w.x = pk2(h0[0], h0[1]); w.y = pk2(h0[2], h0[3]); w.z = pk2(h1[0], h1[1]); w.w = pk2(h1[2], h1[3]);
;         *(u32x4*)(HB + off) = w;
;     __device__ __forceinline__ void operator()(const pg8::f32x4 (&acc)[2][2][4][2], const pg8::Unit& u, int wr, int wc, int fr, int fq) const {
;     ...
;         f.load(row0, col0, pa[0]); f.load(row0, col0 + 128, pa[1]);
; #pragma unroll
;         for (int g = 0; g < 8; ++g) {
;             const int ai = g >> 2, m = g & 3, row = row0 + ai * 128 + m * 16;
;             if (g < 7) { const int row2 = row0 + ((g + 1) >> 2) * 128 + ((g + 1) & 3) * 16;
;                 if (g & 1) { f.load(row2, col0, pa[0]); f.load(row2, col0 + 128, pa[1]); } else { f.load(row2, col0, pb[0]); f.load(row2, col0 + 128, pb[1]); } }
;             float ss = 0.f;
; #pragma unroll
;             for (int bj = 0; bj < 2; ++bj) {
;                 float v[8] = {acc[ai][bj][m][0][0], acc[ai][bj][m][0][1], acc[ai][bj][m][0][2], acc[ai][bj][m][0][3], acc[ai][bj][m][1][0], acc[ai][bj][m][1][1], acc[ai][bj][m][1][2], acc[ai][bj][m][1][3]};
;                 ss += f.apply(row, col0 + bj * 128, v, (g & 1) ? pb[bj] : pa[bj]);
;             }
;             if (F::HAS_SS) { ss += __shfl_xor(ss, 16); ss += __shfl_xor(ss, 32); if (fq == 0) atomicAdd(f.ss + row, ss); }
.LBB0_971:
	s_or_b64 exec, exec, s[2:3]
	v_or_b32_e32 v96, 48, v154
	s_waitcnt lgkmcnt(0)
	v_ashrrev_i32_e32 v97, 31, v96
	v_lshlrev_b64 v[96:97], 12, v[96:97]
	v_lshl_add_u64 v[96:97], s[82:83], 0, v[96:97]
	v_lshl_add_u64 v[104:105], v[152:153], 1, v[96:97]
	s_waitcnt vmcnt(9)
	v_mov_b32_e32 v100, v198
	v_mov_b32_e32 v101, v199
	v_mov_b32_e32 v102, v200
	v_mov_b32_e32 v103, v201
	v_mov_b32_e32 v96, v202
	v_mov_b32_e32 v97, v203
	v_mov_b32_e32 v98, v204
	v_mov_b32_e32 v99, v205
	v_add_u32_e32 v187, 0xa0000, v185
	global_load_dwordx4 v[190:193], v187, s[82:83] offset:256
	v_add_u32_e32 v187, 0xb0000, v185
	global_load_dwordx4 v[194:197], v187, s[82:83]
	global_load_dwordx4 v[198:201], v187, s[82:83] offset:256
	v_lshlrev_b32_e32 v106, 16, v116
	v_and_b32_e32 v107, 0xffff0000, v116
	v_lshlrev_b32_e32 v110, 16, v118
	v_and_b32_e32 v111, 0xffff0000, v118
	v_lshlrev_b32_e32 v108, 16, v117
	v_and_b32_e32 v109, 0xffff0000, v117
	v_lshlrev_b32_e32 v116, 16, v119
	v_and_b32_e32 v117, 0xffff0000, v119
	v_pk_add_f32 v[92:93], v[92:93], v[106:107]
	v_pk_add_f32 v[106:107], v[88:89], v[110:111]
	v_pk_add_f32 v[94:95], v[94:95], v[108:109]
	v_pk_mul_f32 v[88:89], v[106:107], v[106:107]
	v_pk_add_f32 v[108:109], v[90:91], v[116:117]
	v_lshlrev_b32_e32 v124, 16, v114
	v_and_b32_e32 v125, 0xffff0000, v114
	v_pk_fma_f32 v[110:111], v[92:93], v[92:93], v[88:89]
	v_pk_mul_f32 v[88:89], v[108:109], v[108:109]
	v_lshlrev_b32_e32 v118, 16, v112
	v_and_b32_e32 v119, 0xffff0000, v112
	v_lshlrev_b32_e32 v114, 16, v115
	v_and_b32_e32 v115, 0xffff0000, v115
	v_pk_fma_f32 v[90:91], v[94:95], v[94:95], v[88:89]
	v_cvt_pk_bf16_f32 v88, v92, v93
	v_pk_add_f32 v[92:93], v[80:81], v[124:125]
	v_lshlrev_b32_e32 v112, 16, v113
	v_and_b32_e32 v113, 0xffff0000, v113
	v_cvt_pk_bf16_f32 v89, v94, v95
	v_pk_add_f32 v[84:85], v[84:85], v[118:119]
	v_pk_mul_f32 v[80:81], v[92:93], v[92:93]
	v_pk_add_f32 v[94:95], v[82:83], v[114:115]
	v_pk_fma_f32 v[80:81], v[84:85], v[84:85], v[80:81]
	v_pk_add_f32 v[86:87], v[86:87], v[112:113]
	v_pk_mul_f32 v[82:83], v[94:95], v[94:95]
	v_add_f32_e32 v80, v80, v81
	v_pk_fma_f32 v[82:83], v[86:87], v[86:87], v[82:83]
	v_add_f32_e32 v81, v110, v111
	v_add_f32_e32 v80, v82, v80
	v_add_f32_e32 v81, v90, v81
	v_add_f32_e32 v80, v83, v80
	v_add_f32_e32 v81, v91, v81
	v_add_f32_e32 v80, v81, v80
	ds_bpermute_b32 v81, v166, v80
	v_cvt_pk_bf16_f32 v90, v106, v107
	v_cvt_pk_bf16_f32 v91, v108, v109
	v_cvt_pk_bf16_f32 v82, v84, v85
	v_cvt_pk_bf16_f32 v83, v86, v87
	s_waitcnt lgkmcnt(0)
	v_add_f32_e32 v80, v80, v81
	ds_bpermute_b32 v81, v165, v80
	v_cvt_pk_bf16_f32 v84, v92, v93
	v_cvt_pk_bf16_f32 v85, v94, v95
	global_store_dwordx4 v[122:123], v[88:91], off
	global_store_dwordx4 v[122:123], v[82:85], off offset:256
	s_and_saveexec_b64 s[2:3], s[4:5]
	s_cbranch_execz .LBB0_973
	s_waitcnt lgkmcnt(0)
	v_add_f32_e32 v80, v80, v81
	v_mov_b32_e32 v232, v80
.LBB0_973:
	s_or_b64 exec, exec, s[2:3]
	v_add_u32_e32 v88, 0x80, v154
	v_ashrrev_i32_e32 v89, 31, v88
	s_waitcnt lgkmcnt(0)
	v_lshlrev_b64 v[80:81], 12, v[88:89]
	v_lshl_add_u64 v[80:81], s[82:83], 0, v[80:81]
	v_lshl_add_u64 v[90:91], v[152:153], 1, v[80:81]
	s_waitcnt vmcnt(12)
	v_mov_b32_e32 v84, v206
	v_mov_b32_e32 v85, v207
	v_mov_b32_e32 v86, v208
	v_mov_b32_e32 v87, v209
	v_mov_b32_e32 v80, v210
	v_mov_b32_e32 v81, v211
	v_mov_b32_e32 v82, v212
	v_mov_b32_e32 v83, v213
	v_lshlrev_b32_e32 v92, 16, v100
	v_and_b32_e32 v93, 0xffff0000, v100
	v_lshlrev_b32_e32 v94, 16, v101
	v_and_b32_e32 v95, 0xffff0000, v101
	v_lshlrev_b32_e32 v100, 16, v102
	v_and_b32_e32 v101, 0xffff0000, v102
	v_lshlrev_b32_e32 v102, 16, v103
	v_and_b32_e32 v103, 0xffff0000, v103
	v_pk_add_f32 v[76:77], v[76:77], v[92:93]
	v_pk_add_f32 v[92:93], v[72:73], v[100:101]
	v_pk_add_f32 v[78:79], v[78:79], v[94:95]
	v_pk_mul_f32 v[72:73], v[92:93], v[92:93]
	v_pk_add_f32 v[94:95], v[74:75], v[102:103]
	v_lshlrev_b32_e32 v108, 16, v98
	v_and_b32_e32 v109, 0xffff0000, v98
	v_pk_fma_f32 v[100:101], v[76:77], v[76:77], v[72:73]
	v_pk_mul_f32 v[72:73], v[94:95], v[94:95]
	v_lshlrev_b32_e32 v106, 16, v96
	v_and_b32_e32 v107, 0xffff0000, v96
	v_lshlrev_b32_e32 v98, 16, v99
	v_and_b32_e32 v99, 0xffff0000, v99
	v_pk_fma_f32 v[74:75], v[78:79], v[78:79], v[72:73]
	v_cvt_pk_bf16_f32 v72, v76, v77
	v_pk_add_f32 v[76:77], v[64:65], v[108:109]
	v_lshlrev_b32_e32 v96, 16, v97
	v_and_b32_e32 v97, 0xffff0000, v97
	v_cvt_pk_bf16_f32 v73, v78, v79
	v_pk_add_f32 v[68:69], v[68:69], v[106:107]
	v_pk_mul_f32 v[64:65], v[76:77], v[76:77]
	v_pk_add_f32 v[78:79], v[66:67], v[98:99]
	v_pk_fma_f32 v[64:65], v[68:69], v[68:69], v[64:65]
	v_pk_add_f32 v[70:71], v[70:71], v[96:97]
	v_pk_mul_f32 v[66:67], v[78:79], v[78:79]
	v_add_f32_e32 v64, v64, v65
	v_pk_fma_f32 v[66:67], v[70:71], v[70:71], v[66:67]
	v_add_f32_e32 v65, v100, v101
	v_add_f32_e32 v64, v66, v64
	v_add_f32_e32 v65, v74, v65
	v_add_f32_e32 v64, v67, v64
	v_add_f32_e32 v65, v75, v65
	v_add_f32_e32 v64, v65, v64
	ds_bpermute_b32 v65, v166, v64
	v_cvt_pk_bf16_f32 v74, v92, v93
	v_cvt_pk_bf16_f32 v75, v94, v95
	v_cvt_pk_bf16_f32 v66, v68, v69
	v_cvt_pk_bf16_f32 v67, v70, v71
	s_waitcnt lgkmcnt(0)
	v_add_f32_e32 v64, v64, v65
	ds_bpermute_b32 v65, v165, v64
	v_cvt_pk_bf16_f32 v68, v76, v77
	v_cvt_pk_bf16_f32 v69, v78, v79
	global_store_dwordx4 v[104:105], v[72:75], off
	global_store_dwordx4 v[104:105], v[66:69], off offset:256
	s_and_saveexec_b64 s[2:3], s[4:5]
	s_cbranch_execz .LBB0_975
	s_waitcnt lgkmcnt(0)
	v_add_f32_e32 v64, v64, v65
	v_mov_b32_e32 v233, v64
; __device__ __forceinline__ unsigned pk2(float lo, float hi) { f32x2_t v = {lo, hi}; bf16x2_t b = __builtin_convertvector(v, bf16x2_t); return __builtin_bit_cast(unsigned, b); }
;     __device__ __forceinline__ void load(int row, int col, Pre& p) const { const size_t off = (size_t)row * 2048 + col;
;     ...
;         const u32x4 w = *(const u32x4*)(HB + off);
;         p.x0 = (f32x4){bflo(w.x), bfhi(w.x), bflo(w.y), bfhi(w.y)}; p.x1 = (f32x4){bflo(w.z), bfhi(w.z), bflo(w.w), bfhi(w.w)};
;     ...
;         p.x0 = __builtin_nontemporal_load((const f32x4*)(x + off)); p.x1 = __builtin_nontemporal_load((const f32x4*)(x + off + 4));
;     ...
;     }
;     __device__ __forceinline__ float apply(int row, int col, float (&v)[8], const Pre& p) const {
;         const size_t off = (size_t)row * 2048 + col;
;         f32x4 h0, h1; float s = 0.f;
; #pragma unroll
;         for (int i = 0; i < 4; ++i) { h0[i] = p.x0[i] + v[i]; h1[i] = p.x1[i] + v[4 + i]; s += h0[i] * h0[i] + h1[i] * h1[i]; }
;     ...
;         *(f32x4*)(H1 + off) = h0; *(f32x4*)(H1 + off + 4) = h1;
;     ...
;         u32x4 w; w.x = pk2(h0[0], h0[1]); w.y = pk2(h0[2], h0[3]); w.z = pk2(h1[0], h1[1]); w.w = pk2(h1[2], h1[3]);
;         *(u32x4*)(HB + off) = w;
;     __device__ __forceinline__ void operator()(const pg8::f32x4 (&acc)[2][2][4][2], const pg8::Unit& u, int wr, int wc, int fr, int fq) const {
;     ...
;         f.load(row0, col0, pa[0]); f.load(row0, col0 + 128, pa[1]);
; #pragma unroll
;         for (int g = 0; g < 8; ++g) {
;             const int ai = g >> 2, m = g & 3, row = row0 + ai * 128 + m * 16;
;             if (g < 7) { const int row2 = row0 + ((g + 1) >> 2) * 128 + ((g + 1) & 3) * 16;
;                 if (g & 1) { f.load(row2, col0, pa[0]); f.load(row2, col0 + 128, pa[1]); } else { f.load(row2, col0, pb[0]); f.load(row2, col0 + 128, pb[1]); } }
;             float ss = 0.f;
; #pragma unroll
;             for (int bj = 0; bj < 2; ++bj) {
;                 float v[8] = {acc[ai][bj][m][0][0], acc[ai][bj][m][0][1], acc[ai][bj][m][0][2], acc[ai][bj][m][0][3], acc[ai][bj][m][1][0], acc[ai][bj][m][1][1], acc[ai][bj][m][1][2], acc[ai][bj][m][1][3]};
;                 ss += f.apply(row, col0 + bj * 128, v, (g & 1) ? pb[bj] : pa[bj]);
;             }
;             if (F::HAS_SS) { ss += __shfl_xor(ss, 16); ss += __shfl_xor(ss, 32); if (fq == 0) atomicAdd(f.ss + row, ss); }
.LBB0_975:
	s_or_b64 exec, exec, s[2:3]
	v_or_b32_e32 v64, 16, v88
	s_waitcnt lgkmcnt(0)
	v_ashrrev_i32_e32 v65, 31, v64
	v_lshlrev_b64 v[64:65], 12, v[64:65]
	v_lshl_add_u64 v[64:65], s[82:83], 0, v[64:65]
	v_lshl_add_u64 v[72:73], v[152:153], 1, v[64:65]
	s_waitcnt vmcnt(12)
	v_mov_b32_e32 v68, v214
	v_mov_b32_e32 v69, v215
	v_mov_b32_e32 v70, v216
	v_mov_b32_e32 v71, v217
	v_mov_b32_e32 v64, v218
	v_mov_b32_e32 v65, v219
	v_mov_b32_e32 v66, v220
	v_mov_b32_e32 v67, v221
	v_lshlrev_b32_e32 v74, 16, v84
	v_and_b32_e32 v75, 0xffff0000, v84
	v_lshlrev_b32_e32 v78, 16, v86
	v_and_b32_e32 v79, 0xffff0000, v86
	v_lshlrev_b32_e32 v76, 16, v85
	v_and_b32_e32 v77, 0xffff0000, v85
	v_lshlrev_b32_e32 v84, 16, v87
	v_and_b32_e32 v85, 0xffff0000, v87
	v_pk_add_f32 v[60:61], v[60:61], v[74:75]
	v_pk_add_f32 v[74:75], v[56:57], v[78:79]
	v_pk_add_f32 v[62:63], v[62:63], v[76:77]
	v_pk_mul_f32 v[56:57], v[74:75], v[74:75]
	v_pk_add_f32 v[76:77], v[58:59], v[84:85]
	v_lshlrev_b32_e32 v92, 16, v82
	v_and_b32_e32 v93, 0xffff0000, v82
	v_pk_fma_f32 v[78:79], v[60:61], v[60:61], v[56:57]
	v_pk_mul_f32 v[56:57], v[76:77], v[76:77]
	v_lshlrev_b32_e32 v86, 16, v80
	v_and_b32_e32 v87, 0xffff0000, v80
	v_lshlrev_b32_e32 v82, 16, v83
	v_and_b32_e32 v83, 0xffff0000, v83
	v_pk_fma_f32 v[58:59], v[62:63], v[62:63], v[56:57]
	v_cvt_pk_bf16_f32 v56, v60, v61
	v_pk_add_f32 v[60:61], v[48:49], v[92:93]
	v_lshlrev_b32_e32 v80, 16, v81
	v_and_b32_e32 v81, 0xffff0000, v81
	v_cvt_pk_bf16_f32 v57, v62, v63
	v_pk_add_f32 v[52:53], v[52:53], v[86:87]
	v_pk_mul_f32 v[48:49], v[60:61], v[60:61]
	v_pk_add_f32 v[62:63], v[50:51], v[82:83]
	v_pk_fma_f32 v[48:49], v[52:53], v[52:53], v[48:49]
	v_pk_add_f32 v[54:55], v[54:55], v[80:81]
	v_pk_mul_f32 v[50:51], v[62:63], v[62:63]
	v_add_f32_e32 v48, v48, v49
	v_pk_fma_f32 v[50:51], v[54:55], v[54:55], v[50:51]
	v_add_f32_e32 v49, v78, v79
	v_add_f32_e32 v48, v50, v48
	v_add_f32_e32 v49, v58, v49
	v_add_f32_e32 v48, v51, v48
	v_add_f32_e32 v49, v59, v49
	v_add_f32_e32 v48, v49, v48
	ds_bpermute_b32 v49, v166, v48
	v_cvt_pk_bf16_f32 v58, v74, v75
	v_cvt_pk_bf16_f32 v59, v76, v77
	v_cvt_pk_bf16_f32 v50, v52, v53
	v_cvt_pk_bf16_f32 v51, v54, v55
	s_waitcnt lgkmcnt(0)
	v_add_f32_e32 v48, v48, v49
	ds_bpermute_b32 v49, v165, v48
	v_cvt_pk_bf16_f32 v52, v60, v61
	v_cvt_pk_bf16_f32 v53, v62, v63
	global_store_dwordx4 v[90:91], v[56:59], off
	global_store_dwordx4 v[90:91], v[50:53], off offset:256
	s_and_saveexec_b64 s[2:3], s[4:5]
	s_cbranch_execz .LBB0_977
	s_waitcnt lgkmcnt(0)
	v_add_f32_e32 v48, v48, v49
	v_mov_b32_e32 v234, v48
.LBB0_977:
	s_or_b64 exec, exec, s[2:3]
	v_or_b32_e32 v48, 32, v88
	s_waitcnt lgkmcnt(0)
	v_ashrrev_i32_e32 v49, 31, v48
	v_lshlrev_b64 v[48:49], 12, v[48:49]
	v_lshl_add_u64 v[48:49], s[82:83], 0, v[48:49]
	v_lshl_add_u64 v[56:57], v[152:153], 1, v[48:49]
	s_waitcnt vmcnt(8)
	v_mov_b32_e32 v52, v222
	v_mov_b32_e32 v53, v223
	v_mov_b32_e32 v54, v224
	v_mov_b32_e32 v55, v225
	v_mov_b32_e32 v48, v190
	v_mov_b32_e32 v49, v191
	v_mov_b32_e32 v50, v192
	v_mov_b32_e32 v51, v193
	v_lshlrev_b32_e32 v58, 16, v68
	v_and_b32_e32 v59, 0xffff0000, v68
	v_lshlrev_b32_e32 v62, 16, v70
	v_and_b32_e32 v63, 0xffff0000, v70
	v_lshlrev_b32_e32 v60, 16, v69
	v_and_b32_e32 v61, 0xffff0000, v69
	v_lshlrev_b32_e32 v68, 16, v71
	v_and_b32_e32 v69, 0xffff0000, v71
	v_pk_add_f32 v[44:45], v[44:45], v[58:59]
	v_pk_add_f32 v[58:59], v[40:41], v[62:63]
	v_pk_add_f32 v[46:47], v[46:47], v[60:61]
	v_pk_mul_f32 v[40:41], v[58:59], v[58:59]
	v_pk_add_f32 v[60:61], v[42:43], v[68:69]
	v_lshlrev_b32_e32 v74, 16, v66
	v_and_b32_e32 v75, 0xffff0000, v66
	v_pk_fma_f32 v[62:63], v[44:45], v[44:45], v[40:41]
	v_pk_mul_f32 v[40:41], v[60:61], v[60:61]
	v_lshlrev_b32_e32 v70, 16, v64
	v_and_b32_e32 v71, 0xffff0000, v64
	v_lshlrev_b32_e32 v66, 16, v67
	v_and_b32_e32 v67, 0xffff0000, v67
	v_pk_fma_f32 v[42:43], v[46:47], v[46:47], v[40:41]
	v_cvt_pk_bf16_f32 v40, v44, v45
	v_pk_add_f32 v[44:45], v[32:33], v[74:75]
	v_lshlrev_b32_e32 v64, 16, v65
	v_and_b32_e32 v65, 0xffff0000, v65
	v_cvt_pk_bf16_f32 v41, v46, v47
	v_pk_add_f32 v[36:37], v[36:37], v[70:71]
	v_pk_mul_f32 v[32:33], v[44:45], v[44:45]
	v_pk_add_f32 v[46:47], v[34:35], v[66:67]
	v_pk_fma_f32 v[32:33], v[36:37], v[36:37], v[32:33]
	v_pk_add_f32 v[38:39], v[38:39], v[64:65]
	v_pk_mul_f32 v[34:35], v[46:47], v[46:47]
	v_add_f32_e32 v32, v32, v33
	v_pk_fma_f32 v[34:35], v[38:39], v[38:39], v[34:35]
	v_add_f32_e32 v33, v62, v63
	v_add_f32_e32 v32, v34, v32
	v_add_f32_e32 v33, v42, v33
	v_add_f32_e32 v32, v35, v32
	v_add_f32_e32 v33, v43, v33
	v_add_f32_e32 v32, v33, v32
	ds_bpermute_b32 v33, v166, v32
	v_cvt_pk_bf16_f32 v42, v58, v59
	v_cvt_pk_bf16_f32 v43, v60, v61
	v_cvt_pk_bf16_f32 v34, v36, v37
	v_cvt_pk_bf16_f32 v35, v38, v39
	s_waitcnt lgkmcnt(0)
	v_add_f32_e32 v32, v32, v33
	ds_bpermute_b32 v33, v165, v32
	v_cvt_pk_bf16_f32 v36, v44, v45
	v_cvt_pk_bf16_f32 v37, v46, v47
	global_store_dwordx4 v[72:73], v[40:43], off
	global_store_dwordx4 v[72:73], v[34:37], off offset:256
	s_and_saveexec_b64 s[2:3], s[4:5]
	s_cbranch_execz .LBB0_979
	s_waitcnt lgkmcnt(0)
	v_add_f32_e32 v32, v32, v33
	v_mov_b32_e32 v235, v32
; __device__ __forceinline__ unsigned pk2(float lo, float hi) { f32x2_t v = {lo, hi}; bf16x2_t b = __builtin_convertvector(v, bf16x2_t); return __builtin_bit_cast(unsigned, b); }
;     __device__ __forceinline__ void load(int row, int col, Pre& p) const { const size_t off = (size_t)row * 2048 + col;
;     ...
;         const u32x4 w = *(const u32x4*)(HB + off);
;         p.x0 = (f32x4){bflo(w.x), bfhi(w.x), bflo(w.y), bfhi(w.y)}; p.x1 = (f32x4){bflo(w.z), bfhi(w.z), bflo(w.w), bfhi(w.w)};
;     ...
;         p.x0 = __builtin_nontemporal_load((const f32x4*)(x + off)); p.x1 = __builtin_nontemporal_load((const f32x4*)(x + off + 4));
;     ...
;     }
;     __device__ __forceinline__ float apply(int row, int col, float (&v)[8], const Pre& p) const {
;         const size_t off = (size_t)row * 2048 + col;
;         f32x4 h0, h1; float s = 0.f;
; #pragma unroll
;         for (int i = 0; i < 4; ++i) { h0[i] = p.x0[i] + v[i]; h1[i] = p.x1[i] + v[4 + i]; s += h0[i] * h0[i] + h1[i] * h1[i]; }
;     ...
;         *(f32x4*)(H1 + off) = h0; *(f32x4*)(H1 + off + 4) = h1;
;     ...
;         u32x4 w; w.x = pk2(h0[0], h0[1]); w.y = pk2(h0[2], h0[3]); w.z = pk2(h1[0], h1[1]); w.w = pk2(h1[2], h1[3]);
;         *(u32x4*)(HB + off) = w;
;     __device__ __forceinline__ void operator()(const pg8::f32x4 (&acc)[2][2][4][2], const pg8::Unit& u, int wr, int wc, int fr, int fq) const {
;     ...
;         f.load(row0, col0, pa[0]); f.load(row0, col0 + 128, pa[1]);
; #pragma unroll
;         for (int g = 0; g < 8; ++g) {
;             const int ai = g >> 2, m = g & 3, row = row0 + ai * 128 + m * 16;
;             if (g < 7) { const int row2 = row0 + ((g + 1) >> 2) * 128 + ((g + 1) & 3) * 16;
;                 if (g & 1) { f.load(row2, col0, pa[0]); f.load(row2, col0 + 128, pa[1]); } else { f.load(row2, col0, pb[0]); f.load(row2, col0 + 128, pb[1]); } }
;             float ss = 0.f;
; #pragma unroll
;             for (int bj = 0; bj < 2; ++bj) {
;                 float v[8] = {acc[ai][bj][m][0][0], acc[ai][bj][m][0][1], acc[ai][bj][m][0][2], acc[ai][bj][m][0][3], acc[ai][bj][m][1][0], acc[ai][bj][m][1][1], acc[ai][bj][m][1][2], acc[ai][bj][m][1][3]};
;                 ss += f.apply(row, col0 + bj * 128, v, (g & 1) ? pb[bj] : pa[bj]);
;             }
;             if (F::HAS_SS) { ss += __shfl_xor(ss, 16); ss += __shfl_xor(ss, 32); if (fq == 0) atomicAdd(f.ss + row, ss); }
;         }
.LBB0_979:
	s_or_b64 exec, exec, s[2:3]
	v_or_b32_e32 v32, 48, v88
	s_waitcnt lgkmcnt(0)
	v_ashrrev_i32_e32 v33, 31, v32
	v_lshlrev_b64 v[32:33], 12, v[32:33]
	v_lshl_add_u64 v[32:33], s[82:83], 0, v[32:33]
	v_lshl_add_u64 v[40:41], v[152:153], 1, v[32:33]
	s_waitcnt vmcnt(8)
	v_mov_b32_e32 v36, v194
	v_mov_b32_e32 v37, v195
	v_mov_b32_e32 v38, v196
	v_mov_b32_e32 v39, v197
	v_mov_b32_e32 v32, v198
	v_mov_b32_e32 v33, v199
	v_mov_b32_e32 v34, v200
	v_mov_b32_e32 v35, v201
	v_lshlrev_b32_e32 v42, 16, v52
	v_and_b32_e32 v43, 0xffff0000, v52
	v_lshlrev_b32_e32 v46, 16, v54
	v_and_b32_e32 v47, 0xffff0000, v54
	v_lshlrev_b32_e32 v44, 16, v53
	v_and_b32_e32 v45, 0xffff0000, v53
	v_lshlrev_b32_e32 v52, 16, v55
	v_and_b32_e32 v53, 0xffff0000, v55
	v_pk_add_f32 v[28:29], v[28:29], v[42:43]
	v_pk_add_f32 v[42:43], v[24:25], v[46:47]
	v_pk_add_f32 v[30:31], v[30:31], v[44:45]
	v_pk_mul_f32 v[24:25], v[42:43], v[42:43]
	v_pk_add_f32 v[44:45], v[26:27], v[52:53]
	v_lshlrev_b32_e32 v58, 16, v50
	v_and_b32_e32 v59, 0xffff0000, v50
	v_pk_fma_f32 v[46:47], v[28:29], v[28:29], v[24:25]
	v_pk_mul_f32 v[24:25], v[44:45], v[44:45]
	v_lshlrev_b32_e32 v54, 16, v48
	v_and_b32_e32 v55, 0xffff0000, v48
	v_lshlrev_b32_e32 v50, 16, v51
	v_and_b32_e32 v51, 0xffff0000, v51
	v_pk_fma_f32 v[26:27], v[30:31], v[30:31], v[24:25]
	v_cvt_pk_bf16_f32 v24, v28, v29
	v_pk_add_f32 v[28:29], v[16:17], v[58:59]
	v_lshlrev_b32_e32 v48, 16, v49
	v_and_b32_e32 v49, 0xffff0000, v49
	v_cvt_pk_bf16_f32 v25, v30, v31
	v_pk_add_f32 v[20:21], v[20:21], v[54:55]
	v_pk_mul_f32 v[16:17], v[28:29], v[28:29]
	v_pk_add_f32 v[30:31], v[18:19], v[50:51]
	v_pk_fma_f32 v[16:17], v[20:21], v[20:21], v[16:17]
	v_pk_add_f32 v[22:23], v[22:23], v[48:49]
	v_pk_mul_f32 v[18:19], v[30:31], v[30:31]
	v_add_f32_e32 v16, v16, v17
	v_pk_fma_f32 v[18:19], v[22:23], v[22:23], v[18:19]
	v_add_f32_e32 v17, v46, v47
	v_add_f32_e32 v16, v18, v16
	v_add_f32_e32 v17, v26, v17
	v_add_f32_e32 v16, v19, v16
	v_add_f32_e32 v17, v27, v17
	v_add_f32_e32 v16, v17, v16
	ds_bpermute_b32 v17, v166, v16
	v_cvt_pk_bf16_f32 v26, v42, v43
	v_cvt_pk_bf16_f32 v27, v44, v45
	v_cvt_pk_bf16_f32 v18, v20, v21
	v_cvt_pk_bf16_f32 v19, v22, v23
	s_waitcnt lgkmcnt(0)
	v_add_f32_e32 v16, v16, v17
	ds_bpermute_b32 v17, v165, v16
	v_cvt_pk_bf16_f32 v20, v28, v29
	v_cvt_pk_bf16_f32 v21, v30, v31
	global_store_dwordx4 v[56:57], v[24:27], off
	global_store_dwordx4 v[56:57], v[18:21], off offset:256
	s_and_saveexec_b64 s[2:3], s[4:5]
	s_cbranch_execz .LBB0_981
	s_waitcnt lgkmcnt(0)
	v_add_f32_e32 v16, v16, v17
	v_mov_b32_e32 v236, v16
.LBB0_981:
	s_or_b64 exec, exec, s[2:3]
	v_lshlrev_b32_e32 v16, 16, v36
	s_waitcnt lgkmcnt(0)
	v_and_b32_e32 v17, 0xffff0000, v36
	v_lshlrev_b32_e32 v20, 16, v38
	v_and_b32_e32 v21, 0xffff0000, v38
	v_lshlrev_b32_e32 v18, 16, v37
	v_and_b32_e32 v19, 0xffff0000, v37
	v_lshlrev_b32_e32 v22, 16, v39
	v_and_b32_e32 v23, 0xffff0000, v39
	v_pk_add_f32 v[12:13], v[12:13], v[16:17]
	v_pk_add_f32 v[16:17], v[8:9], v[20:21]
	v_pk_add_f32 v[14:15], v[14:15], v[18:19]
	v_pk_mul_f32 v[8:9], v[16:17], v[16:17]
	v_pk_add_f32 v[18:19], v[10:11], v[22:23]
	v_lshlrev_b32_e32 v28, 16, v34
	v_and_b32_e32 v29, 0xffff0000, v34
	v_pk_fma_f32 v[20:21], v[12:13], v[12:13], v[8:9]
	v_pk_mul_f32 v[8:9], v[18:19], v[18:19]
	v_lshlrev_b32_e32 v24, 16, v32
	v_and_b32_e32 v25, 0xffff0000, v32
	v_lshlrev_b32_e32 v30, 16, v35
	v_and_b32_e32 v31, 0xffff0000, v35
	v_pk_fma_f32 v[10:11], v[14:15], v[14:15], v[8:9]
	v_cvt_pk_bf16_f32 v8, v12, v13
	v_pk_add_f32 v[12:13], v[0:1], v[28:29]
	v_lshlrev_b32_e32 v26, 16, v33
	v_and_b32_e32 v27, 0xffff0000, v33
	v_cvt_pk_bf16_f32 v9, v14, v15
	v_pk_add_f32 v[4:5], v[4:5], v[24:25]
	v_pk_mul_f32 v[0:1], v[12:13], v[12:13]
	v_pk_add_f32 v[14:15], v[2:3], v[30:31]
	v_pk_fma_f32 v[0:1], v[4:5], v[4:5], v[0:1]
	v_pk_add_f32 v[6:7], v[6:7], v[26:27]
	v_pk_mul_f32 v[2:3], v[14:15], v[14:15]
	v_add_f32_e32 v0, v0, v1
	v_pk_fma_f32 v[2:3], v[6:7], v[6:7], v[2:3]
	v_add_f32_e32 v1, v20, v21
	v_add_f32_e32 v0, v2, v0
	v_add_f32_e32 v1, v10, v1
	v_add_f32_e32 v0, v3, v0
	v_add_f32_e32 v1, v11, v1
	v_add_f32_e32 v0, v1, v0
	ds_bpermute_b32 v1, v166, v0
	v_cvt_pk_bf16_f32 v10, v16, v17
	v_cvt_pk_bf16_f32 v11, v18, v19
	v_cvt_pk_bf16_f32 v2, v4, v5
	v_cvt_pk_bf16_f32 v3, v6, v7
	s_waitcnt lgkmcnt(0)
	v_add_f32_e32 v0, v0, v1
	ds_bpermute_b32 v1, v165, v0
	v_cvt_pk_bf16_f32 v4, v12, v13
	v_cvt_pk_bf16_f32 v5, v14, v15
	global_store_dwordx4 v[40:41], v[8:11], off
	global_store_dwordx4 v[40:41], v[2:5], off offset:256
	s_and_saveexec_b64 s[2:3], s[4:5]
	s_cbranch_execz .LBB0_983
	s_waitcnt lgkmcnt(0)
	v_add_f32_e32 v0, v0, v1
	v_mov_b32_e32 v237, v0
	global_atomic_add_f32 v[120:121], v230, off
	global_atomic_add_f32 v[120:121], v231, off offset:64
	global_atomic_add_f32 v[120:121], v232, off offset:128
	global_atomic_add_f32 v[120:121], v233, off offset:192
	global_atomic_add_f32 v[120:121], v234, off offset:512
	global_atomic_add_f32 v[120:121], v235, off offset:576
	global_atomic_add_f32 v[120:121], v236, off offset:640
	global_atomic_add_f32 v[120:121], v237, off offset:704
